# row-statistics exchange: L1 invalidate after the poll removed (slots are read with sc1 loads)
# speedup vs baseline: 1.0375x; 1.0099x over previous
;     __device__ __forceinline__ bool finish(const Unit& u, PG8_LAS unsigned char* lds, int wid, int lane) const {
;     ...
;         if (wid == 0) {
;             bool dead = false; const unsigned long long t0 = __builtin_amdgcn_s_memrealtime();
;             for (;;) {
;                 if ((unsigned)__builtin_amdgcn_readfirstlane(__hip_atomic_load(cnt + 64 * u.pm, __ATOMIC_RELAXED, __HIP_MEMORY_SCOPE_AGENT)) >= 64u) break;
;                 if (__builtin_amdgcn_s_memrealtime() - t0 > 2000000ull) {
;                     if (lane == 0) { unsigned expect = 0u; __hip_atomic_compare_exchange_strong(tmo + 1, &expect, code | (unsigned)(u.pm & 0xff), __ATOMIC_RELAXED, __ATOMIC_RELAXED, __HIP_MEMORY_SCOPE_AGENT);
;                                      __hip_atomic_store(tmo, 1u, __ATOMIC_RELAXED, __HIP_MEMORY_SCOPE_AGENT); }
;                     dead = true; break; }
;                 __builtin_amdgcn_s_sleep(2);
;             }
;             __builtin_amdgcn_fence(__ATOMIC_ACQUIRE, "agent");
;             if (lane == 0) flag[0] = dead ? 1u : 0u;
;         }
.LBB0_846:
	s_andn2_b64 vcc, exec, s[16:17]
	s_cbranch_vccz .LBB0_852
	s_waitcnt lgkmcnt(0)
	s_and_saveexec_b64 s[12:13], s[44:45]
	s_xor_b64 s[12:13], exec, s[12:13]
	s_cbranch_execz .LBB0_849
.LBB0_849:
	s_or_saveexec_b64 s[14:15], s[12:13]
	s_mov_b64 s[12:13], 0
	s_xor_b64 exec, exec, s[14:15]
	s_cbranch_execz .LBB0_851
	s_and_b32 s9, s30, 0xff
	s_or_b32 s9, s9, 0x700
	v_mov_b32_e32 v194, s9
	global_atomic_cmpswap v195, v[194:195], s[78:79]
	s_mov_b64 s[12:13], exec
	global_store_dword v195, v216, s[72:73] sc1

;     __device__ __forceinline__ bool finish(const Unit& u, PG8_LAS unsigned char* lds, int wid, int lane) const {
;     ...
;             __builtin_amdgcn_fence(__ATOMIC_ACQUIRE, "agent");
;             if (lane == 0) flag[0] = dead ? 1u : 0u;
.LBB0_853:
	s_waitcnt vmcnt(0)
	s_and_b64 exec, exec, s[42:43]
	v_cndmask_b32_e64 v138, 0, 1, s[14:15]
	ds_write_b32 v195, v138 offset:5120

;     __device__ __forceinline__ bool finish(const Unit& u, PG8_LAS unsigned char* lds, int wid, int lane) const {
;     ...
;         if (wid == 0) {
;             bool dead = false; const unsigned long long t0 = __builtin_amdgcn_s_memrealtime();
;             for (;;) {
;                 if ((unsigned)__builtin_amdgcn_readfirstlane(__hip_atomic_load(cnt + 64 * u.pm, __ATOMIC_RELAXED, __HIP_MEMORY_SCOPE_AGENT)) >= 64u) break;
;                 if (__builtin_amdgcn_s_memrealtime() - t0 > 2000000ull) {
;                     if (lane == 0) { unsigned expect = 0u; __hip_atomic_compare_exchange_strong(tmo + 1, &expect, code | (unsigned)(u.pm & 0xff), __ATOMIC_RELAXED, __ATOMIC_RELAXED, __HIP_MEMORY_SCOPE_AGENT);
;                                      __hip_atomic_store(tmo, 1u, __ATOMIC_RELAXED, __HIP_MEMORY_SCOPE_AGENT); }
;                     dead = true; break; }
;                 __builtin_amdgcn_s_sleep(2);
;             }
;             __builtin_amdgcn_fence(__ATOMIC_ACQUIRE, "agent");
;             if (lane == 0) flag[0] = dead ? 1u : 0u;
;         }
.LBB0_958:
	s_andn2_b64 vcc, exec, s[8:9]
	s_cbranch_vccz .LBB0_967
	s_waitcnt lgkmcnt(0)
	s_and_saveexec_b64 s[0:1], s[44:45]
	s_xor_b64 s[0:1], exec, s[0:1]
	s_cbranch_execz .LBB0_961
.LBB0_961:
	s_or_saveexec_b64 s[6:7], s[0:1]
	s_mov_b64 s[0:1], 0
	s_xor_b64 exec, exec, s[6:7]
	s_cbranch_execz .LBB0_963
	s_and_b32 s0, s30, 0xff
	s_bitset1_b32 s0, 11
	v_mov_b32_e32 v194, s0
	global_atomic_cmpswap v195, v[194:195], s[78:79]
	s_mov_b64 s[0:1], exec
	global_store_dword v195, v216, s[72:73] sc1

;     __device__ __forceinline__ bool finish(const Unit& u, PG8_LAS unsigned char* lds, int wid, int lane) const {
;     ...
;             __builtin_amdgcn_fence(__ATOMIC_ACQUIRE, "agent");
;             if (lane == 0) flag[0] = dead ? 1u : 0u;
.LBB0_968:
	s_waitcnt vmcnt(0)
	s_and_b64 exec, exec, s[42:43]
	v_cndmask_b32_e64 v130, 0, 1, s[6:7]
	ds_write_b32 v195, v130 offset:5120

;     __device__ __forceinline__ bool finish(const Unit& u, PG8_LAS unsigned char* lds, int wid, int lane) const {
;     ...
;         if (wid == 0) {
;             bool dead = false; const unsigned long long t0 = __builtin_amdgcn_s_memrealtime();
;             for (;;) {
;                 if ((unsigned)__builtin_amdgcn_readfirstlane(__hip_atomic_load(cnt + 64 * u.pm, __ATOMIC_RELAXED, __HIP_MEMORY_SCOPE_AGENT)) >= 64u) break;
;                 if (__builtin_amdgcn_s_memrealtime() - t0 > 2000000ull) {
;                     if (lane == 0) { unsigned expect = 0u; __hip_atomic_compare_exchange_strong(tmo + 1, &expect, code | (unsigned)(u.pm & 0xff), __ATOMIC_RELAXED, __ATOMIC_RELAXED, __HIP_MEMORY_SCOPE_AGENT);
;                                      __hip_atomic_store(tmo, 1u, __ATOMIC_RELAXED, __HIP_MEMORY_SCOPE_AGENT); }
;                     dead = true; break; }
;                 __builtin_amdgcn_s_sleep(2);
;             }
;             __builtin_amdgcn_fence(__ATOMIC_ACQUIRE, "agent");
;             if (lane == 0) flag[0] = dead ? 1u : 0u;
;         }
.LBB0_1832:
	s_andn2_b64 vcc, exec, s[14:15]
	s_cbranch_vccz .LBB0_1838
	s_waitcnt lgkmcnt(0)
	s_and_saveexec_b64 s[10:11], s[44:45]
	s_xor_b64 s[10:11], exec, s[10:11]
	s_cbranch_execz .LBB0_1835
.LBB0_1835:
	s_or_saveexec_b64 s[12:13], s[10:11]
	s_mov_b64 s[10:11], 0
	s_xor_b64 exec, exec, s[12:13]
	s_cbranch_execz .LBB0_1837
	s_and_b32 s5, s0, 0xff
	s_or_b32 s5, s5, 0x700
	v_mov_b32_e32 v194, s5
	global_atomic_cmpswap v195, v[194:195], s[78:79]
	s_mov_b64 s[10:11], exec
	global_store_dword v195, v216, s[72:73] sc1

;     __device__ __forceinline__ bool finish(const Unit& u, PG8_LAS unsigned char* lds, int wid, int lane) const {
;     ...
;             __builtin_amdgcn_fence(__ATOMIC_ACQUIRE, "agent");
;             if (lane == 0) flag[0] = dead ? 1u : 0u;
.LBB0_1839:
	s_waitcnt vmcnt(0)
	s_and_b64 exec, exec, s[42:43]
	v_cndmask_b32_e64 v130, 0, 1, s[12:13]
	ds_write_b32 v195, v130 offset:5120

;     __device__ __forceinline__ bool finish(const Unit& u, PG8_LAS unsigned char* lds, int wid, int lane) const {
;     ...
;         if (wid == 0) {
;             bool dead = false; const unsigned long long t0 = __builtin_amdgcn_s_memrealtime();
;             for (;;) {
;                 if ((unsigned)__builtin_amdgcn_readfirstlane(__hip_atomic_load(cnt + 64 * u.pm, __ATOMIC_RELAXED, __HIP_MEMORY_SCOPE_AGENT)) >= 64u) break;
;                 if (__builtin_amdgcn_s_memrealtime() - t0 > 2000000ull) {
;                     if (lane == 0) { unsigned expect = 0u; __hip_atomic_compare_exchange_strong(tmo + 1, &expect, code | (unsigned)(u.pm & 0xff), __ATOMIC_RELAXED, __ATOMIC_RELAXED, __HIP_MEMORY_SCOPE_AGENT);
;                                      __hip_atomic_store(tmo, 1u, __ATOMIC_RELAXED, __HIP_MEMORY_SCOPE_AGENT); }
;                     dead = true; break; }
;                 __builtin_amdgcn_s_sleep(2);
;             }
;             __builtin_amdgcn_fence(__ATOMIC_ACQUIRE, "agent");
;             if (lane == 0) flag[0] = dead ? 1u : 0u;
;         }
.LBB0_1872:
	s_andn2_b64 vcc, exec, s[10:11]
	s_cbranch_vccz .LBB0_1878
	s_waitcnt lgkmcnt(0)
	s_and_saveexec_b64 s[4:5], s[44:45]
	s_xor_b64 s[4:5], exec, s[4:5]
	s_cbranch_execz .LBB0_1875
.LBB0_1875:
	s_or_saveexec_b64 s[6:7], s[4:5]
	s_mov_b64 s[4:5], 0
	s_xor_b64 exec, exec, s[6:7]
	s_cbranch_execz .LBB0_1877
	s_and_b32 s0, s0, 0xff
	s_bitset1_b32 s0, 11
	v_mov_b32_e32 v194, s0
	global_atomic_cmpswap v195, v[194:195], s[78:79]
	s_mov_b64 s[4:5], exec
	global_store_dword v195, v216, s[72:73] sc1

;     __device__ __forceinline__ bool finish(const Unit& u, PG8_LAS unsigned char* lds, int wid, int lane) const {
;     ...
;             __builtin_amdgcn_fence(__ATOMIC_ACQUIRE, "agent");
;             if (lane == 0) flag[0] = dead ? 1u : 0u;
.LBB0_1879:
	s_waitcnt vmcnt(0)
	s_and_b64 exec, exec, s[42:43]
	v_cndmask_b32_e64 v130, 0, 1, s[0:1]
	ds_write_b32 v195, v130 offset:5120

;     __device__ __forceinline__ bool finish(const Unit& u, PG8_LAS unsigned char* lds, int wid, int lane) const {
;     ...
;         if (wid == 0) {
;             bool dead = false; const unsigned long long t0 = __builtin_amdgcn_s_memrealtime();
;             for (;;) {
;                 if ((unsigned)__builtin_amdgcn_readfirstlane(__hip_atomic_load(cnt + 64 * u.pm, __ATOMIC_RELAXED, __HIP_MEMORY_SCOPE_AGENT)) >= 64u) break;
;                 if (__builtin_amdgcn_s_memrealtime() - t0 > 2000000ull) {
;                     if (lane == 0) { unsigned expect = 0u; __hip_atomic_compare_exchange_strong(tmo + 1, &expect, code | (unsigned)(u.pm & 0xff), __ATOMIC_RELAXED, __ATOMIC_RELAXED, __HIP_MEMORY_SCOPE_AGENT);
;                                      __hip_atomic_store(tmo, 1u, __ATOMIC_RELAXED, __HIP_MEMORY_SCOPE_AGENT); }
;                     dead = true; break; }
;                 __builtin_amdgcn_s_sleep(2);
;             }
;             __builtin_amdgcn_fence(__ATOMIC_ACQUIRE, "agent");
;             if (lane == 0) flag[0] = dead ? 1u : 0u;
;         }
.LBB0_2363:
	s_andn2_b64 vcc, exec, s[16:17]
	s_cbranch_vccz .LBB0_2369
	s_waitcnt lgkmcnt(0)
	s_and_saveexec_b64 s[6:7], s[46:47]
	s_xor_b64 s[6:7], exec, s[6:7]
	s_cbranch_execz .LBB0_2366
.LBB0_2366:
	s_or_saveexec_b64 s[14:15], s[6:7]
	s_mov_b64 s[6:7], 0
	s_xor_b64 exec, exec, s[14:15]
	s_cbranch_execz .LBB0_2368
	s_and_b32 s6, s48, 0xff
	s_or_b32 s6, s6, 0x700
	v_mov_b32_e32 v194, s6
	global_atomic_cmpswap v195, v[194:195], s[78:79]
	s_mov_b64 s[6:7], exec
	global_store_dword v195, v216, s[72:73] sc1

;     __device__ __forceinline__ bool finish(const Unit& u, PG8_LAS unsigned char* lds, int wid, int lane) const {
;     ...
;             __builtin_amdgcn_fence(__ATOMIC_ACQUIRE, "agent");
;             if (lane == 0) flag[0] = dead ? 1u : 0u;
.LBB0_2370:
	s_waitcnt vmcnt(0)
	s_and_b64 exec, exec, s[44:45]
	v_cndmask_b32_e64 v130, 0, 1, s[14:15]
	ds_write_b32 v195, v130 offset:5120

;     __device__ __forceinline__ bool finish(const Unit& u, PG8_LAS unsigned char* lds, int wid, int lane) const {
;     ...
;         if (wid == 0) {
;             bool dead = false; const unsigned long long t0 = __builtin_amdgcn_s_memrealtime();
;             for (;;) {
;                 if ((unsigned)__builtin_amdgcn_readfirstlane(__hip_atomic_load(cnt + 64 * u.pm, __ATOMIC_RELAXED, __HIP_MEMORY_SCOPE_AGENT)) >= 64u) break;
;                 if (__builtin_amdgcn_s_memrealtime() - t0 > 2000000ull) {
;                     if (lane == 0) { unsigned expect = 0u; __hip_atomic_compare_exchange_strong(tmo + 1, &expect, code | (unsigned)(u.pm & 0xff), __ATOMIC_RELAXED, __ATOMIC_RELAXED, __HIP_MEMORY_SCOPE_AGENT);
;                                      __hip_atomic_store(tmo, 1u, __ATOMIC_RELAXED, __HIP_MEMORY_SCOPE_AGENT); }
;                     dead = true; break; }
;                 __builtin_amdgcn_s_sleep(2);
;             }
;             __builtin_amdgcn_fence(__ATOMIC_ACQUIRE, "agent");
;             if (lane == 0) flag[0] = dead ? 1u : 0u;
;         }
.LBB0_2404:
	s_andn2_b64 vcc, exec, s[10:11]
	s_cbranch_vccz .LBB0_2410
	s_waitcnt lgkmcnt(0)
	s_and_saveexec_b64 s[0:1], s[46:47]
	s_xor_b64 s[0:1], exec, s[0:1]
	s_cbranch_execz .LBB0_2407
.LBB0_2407:
	s_or_saveexec_b64 s[6:7], s[0:1]
	s_mov_b64 s[0:1], 0
	s_xor_b64 exec, exec, s[6:7]
	s_cbranch_execz .LBB0_2409
	s_and_b32 s0, s48, 0xff
	s_bitset1_b32 s0, 11
	v_mov_b32_e32 v194, s0
	global_atomic_cmpswap v195, v[194:195], s[78:79]
	s_mov_b64 s[0:1], exec
	global_store_dword v195, v216, s[72:73] sc1

;     __device__ __forceinline__ bool finish(const Unit& u, PG8_LAS unsigned char* lds, int wid, int lane) const {
;     ...
;             __builtin_amdgcn_fence(__ATOMIC_ACQUIRE, "agent");
;             if (lane == 0) flag[0] = dead ? 1u : 0u;
.LBB0_2411:
	s_waitcnt vmcnt(0)
	s_and_b64 exec, exec, s[44:45]
	v_cndmask_b32_e64 v130, 0, 1, s[6:7]
	ds_write_b32 v195, v130 offset:5120
